# v53 + yt_phase loop software-pipelined (next item's loads issued before current item's LDS read-back/stores; no store-ack wait)
# baseline (speedup 1.0000x reference)
; #define LAS __attribute__((address_space(3)))
; #define GAS __attribute__((address_space(1)))
; __device__ __forceinline__ void yt_phase(Frame& F, int wblk, int nblk) {
;     ...
;         for (int it = wblk; it < 144 * 4; it += nblk) {
;             const int tile = it >> 2, c0 = (it & 3) * 128, row0 = tile * 64;
;             int t0, L; const GAS bf16_t* src;
;             if (row0 < MC) { const int sq = row0 >> 8; t0 = row0 & 255; L = CTXL; src = (const GAS bf16_t*)(F.ws + WS_YBTC) + (size_t)sq * 512 * CTXL; }
;             else { const int r = row0 - MC, sq = r >> 11; t0 = r & 2047; L = SEQ; src = (const GAS bf16_t*)(F.ws + WS_YBTL) + (size_t)sq * 512 * SEQ; }
;             __syncthreads();
;             { const int c = F.tid >> 2, seg = F.tid & 3; const GAS bf16_t* sp = src + (size_t)(c0 + c) * L + t0 + 16 * seg;
;               *(LAS u32x4*)(LT + c * 72 + 16 * seg) = *(const GAS u32x4*)sp; *(LAS u32x4*)(LT + c * 72 + 16 * seg + 8) = *(const GAS u32x4*)(sp + 8); }
;             __syncthreads();
; #pragma unroll
;             for (int k = 0; k < 4; ++k) { const int tl = (F.tid >> 5) + 16 * k, c4 = (F.tid & 31) * 4;
;                 const unsigned v0 = LT[(c4 + 0) * 72 + tl], v1 = LT[(c4 + 1) * 72 + tl], v2 = LT[(c4 + 2) * 72 + tl], v3 = LT[(c4 + 3) * 72 + tl];
;                 u32x2 w; w.x = v0 | (v1 << 16); w.y = v2 | (v3 << 16);
;                 *(GAS u32x2*)(Yw + (size_t)(row0 + tl) * D + 512 + c0 + c4) = w; }
;         }
.LBB0_1025:
	v_readlane_b32 s0, v254, 42
	v_readlane_b32 s1, v254, 43
	s_and_b64 vcc, exec, s[0:1]
	s_cbranch_vccz .LBB0_1035
	v_readlane_b32 s4, v254, 44
	v_readlane_b32 s5, v254, 45
	s_load_dwordx2 s[0:1], s[12:13], 0x130
	s_andn2_b64 vcc, exec, s[4:5]
	s_waitcnt lgkmcnt(0)
	s_cbranch_vccnz .LBB0_1034
	v_lshlrev_b32_e32 v0, 4, v184
	s_waitcnt vmcnt(0)
	v_ashrrev_i32_e32 v2, 2, v184
	v_and_b32_e32 v0, 48, v0
	s_movk_i32 s4, 0x90
	v_mul_lo_u32 v1, v2, s4
	v_lshlrev_b32_e32 v3, 1, v0
	v_add3_u32 v3, 0, v1, v3
	v_lshlrev_b32_e32 v1, 2, v184
	v_ashrrev_i32_e32 v4, 5, v184
	s_waitcnt vmcnt(22)
	v_and_b32_e32 v6, 0x7c, v1
	v_mul_u32_u24_e32 v1, 0x90, v6
	v_lshlrev_b32_e32 v5, 1, v4
	v_add3_u32 v5, 0, v1, v5
	v_lshlrev_b32_e32 v202, 1, v0
	v_lshlrev_b32_e32 v0, 1, v6
	v_readlane_b32 s4, v255, 27
	v_readlane_b32 s5, v255, 25
	v_readlane_b32 s24, v255, 23
	v_readlane_b32 s25, v255, 20
	s_and_b32 s26, s5, 0x7fffffc0
	s_cmpk_gt_u32 s26, 0x3ff
	s_mov_b64 s[8:9], -1
	s_cbranch_scc0 .Lyt_h32a
	s_add_i32 s7, s26, 0xfffffc00
	s_and_b32 s6, s7, 0x7c0
	s_lshr_b32 s7, s7, 2
	s_and_b32 s56, s7, 0x3ffffe00
	s_mov_b64 s[8:9], 0
.Lyt_h32a:
	s_andn2_b64 vcc, exec, s[8:9]
	s_cbranch_vccz .Lyt_h28a
	s_mov_b64 s[8:9], 0x800
	s_mov_b64 s[18:19], 0x3b400000
	s_mov_b64 s[10:11], 12
	s_branch .Lyt_h29a
.Lyt_h28a:
	s_and_b32 s6, s5, 0xc0
	s_mov_b64 s[8:9], 0x100
	s_mov_b64 s[18:19], 0x3bc00000
	s_mov_b64 s[10:11], 18
	s_mov_b32 s56, s25
.Lyt_h29a:
	s_and_b32 s27, s4, 0x180
	s_add_u32 s7, s0, s18
	s_addc_u32 s9, s1, s19
	s_lshl_b64 s[10:11], s[56:57], s10
	s_add_u32 s10, s7, s10
	v_add_u32_e32 v1, s27, v2
	s_addc_u32 s11, s9, s11
	v_mad_i64_i32 v[6:7], s[8:9], s8, v1, 0
	v_lshl_add_u64 v[6:7], v[6:7], 1, s[10:11]
	s_mov_b32 s7, s57
	v_lshl_add_u64 v[6:7], s[6:7], 1, v[6:7]
	v_lshl_add_u64 v[10:11], v[6:7], 0, v[202:203]
	global_load_dwordx4 v[100:103], v[10:11], off offset:16
	global_load_dwordx4 v[104:107], v[10:11], off
	v_add_u32_e32 v8, s26, v4
	v_ashrrev_i32_e32 v9, 31, v8
	v_lshlrev_b64 v[110:111], 12, v[8:9]
	s_lshl_b32 s56, s27, 1
	v_lshl_add_u64 v[110:111], s[0:1], 0, v[110:111]
	v_mov_b32_e32 v1, v203
	v_lshl_add_u64 v[110:111], v[110:111], 0, s[56:57]
	v_lshl_add_u64 v[110:111], v[110:111], 0, v[0:1]
	v_add_co_u32_e32 v110, vcc, 0x37e00000, v110
	s_nop 1
	v_addc_co_u32_e32 v111, vcc, 0, v111, vcc
	s_add_i32 s25, s25, 7
	s_addk_i32 s24, 0x70
	s_addk_i32 s5, 0x700
	s_addk_i32 s4, 0x3800
	s_cmpk_lt_i32 s24, 0x1d0
	s_cselect_b32 s100, 1, 0
	s_waitcnt vmcnt(0)
.Lyt_loop:
	v_mov_b32_e32 v108, v110
	v_mov_b32_e32 v109, v111
	s_barrier
	ds_write_b128 v3, v[104:107]
	ds_write_b128 v3, v[100:103] offset:16
	s_waitcnt lgkmcnt(0)
	s_barrier
	s_mov_b32 s101, s100
	s_cmp_eq_u32 s100, 0
	s_cbranch_scc1 .Lyt_nofetch
	s_and_b32 s26, s5, 0x7fffffc0
	s_cmpk_gt_u32 s26, 0x3ff
	s_mov_b64 s[8:9], -1
	s_cbranch_scc0 .Lyt_h32b
	s_add_i32 s7, s26, 0xfffffc00
	s_and_b32 s6, s7, 0x7c0
	s_lshr_b32 s7, s7, 2
	s_and_b32 s56, s7, 0x3ffffe00
	s_mov_b64 s[8:9], 0
.Lyt_h32b:
	s_andn2_b64 vcc, exec, s[8:9]
	s_cbranch_vccz .Lyt_h28b
	s_mov_b64 s[8:9], 0x800
	s_mov_b64 s[18:19], 0x3b400000
	s_mov_b64 s[10:11], 12
	s_branch .Lyt_h29b
.Lyt_h28b:
	s_and_b32 s6, s5, 0xc0
	s_mov_b64 s[8:9], 0x100
	s_mov_b64 s[18:19], 0x3bc00000
	s_mov_b64 s[10:11], 18
	s_mov_b32 s56, s25
.Lyt_h29b:
	s_and_b32 s27, s4, 0x180
	s_add_u32 s7, s0, s18
	s_addc_u32 s9, s1, s19
	s_lshl_b64 s[10:11], s[56:57], s10
	s_add_u32 s10, s7, s10
	v_add_u32_e32 v1, s27, v2
	s_addc_u32 s11, s9, s11
	v_mad_i64_i32 v[6:7], s[8:9], s8, v1, 0
	v_lshl_add_u64 v[6:7], v[6:7], 1, s[10:11]
	s_mov_b32 s7, s57
	v_lshl_add_u64 v[6:7], s[6:7], 1, v[6:7]
	v_lshl_add_u64 v[10:11], v[6:7], 0, v[202:203]
	global_load_dwordx4 v[100:103], v[10:11], off offset:16
	global_load_dwordx4 v[104:107], v[10:11], off
	v_add_u32_e32 v8, s26, v4
	v_ashrrev_i32_e32 v9, 31, v8
	v_lshlrev_b64 v[110:111], 12, v[8:9]
	s_lshl_b32 s56, s27, 1
	v_lshl_add_u64 v[110:111], s[0:1], 0, v[110:111]
	v_mov_b32_e32 v1, v203
	v_lshl_add_u64 v[110:111], v[110:111], 0, s[56:57]
	v_lshl_add_u64 v[110:111], v[110:111], 0, v[0:1]
	v_add_co_u32_e32 v110, vcc, 0x37e00000, v110
	s_nop 1
	v_addc_co_u32_e32 v111, vcc, 0, v111, vcc
	s_add_i32 s25, s25, 7
	s_addk_i32 s24, 0x70
	s_addk_i32 s5, 0x700
	s_addk_i32 s4, 0x3800
	s_cmpk_lt_i32 s24, 0x1d0
	s_cselect_b32 s100, 1, 0
.Lyt_nofetch:
	ds_read_u16 v112, v5
	ds_read_u16 v113, v5 offset:144
	ds_read_u16 v114, v5 offset:288
	ds_read_u16 v115, v5 offset:432
	ds_read_u16 v116, v5 offset:32
	ds_read_u16 v117, v5 offset:176
	ds_read_u16 v118, v5 offset:320
	ds_read_u16 v119, v5 offset:464
	ds_read_u16 v120, v5 offset:64
	ds_read_u16 v121, v5 offset:208
	ds_read_u16 v122, v5 offset:352
	ds_read_u16 v123, v5 offset:496
	ds_read_u16 v124, v5 offset:96
	ds_read_u16 v125, v5 offset:240
	ds_read_u16 v126, v5 offset:384
	ds_read_u16 v127, v5 offset:528
	s_waitcnt lgkmcnt(12)
	v_lshl_or_b32 v112, v113, 16, v112
	v_lshl_or_b32 v113, v115, 16, v114
	global_store_dwordx2 v[108:109], v[112:113], off offset:1024
	s_waitcnt lgkmcnt(8)
	v_lshl_or_b32 v116, v117, 16, v116
	v_lshl_or_b32 v117, v119, 16, v118
	v_add_co_u32_e32 v92, vcc, 0x10000, v108
	s_nop 1
	v_addc_co_u32_e32 v93, vcc, 0, v109, vcc
	global_store_dwordx2 v[92:93], v[116:117], off offset:1024
	s_waitcnt lgkmcnt(4)
	v_lshl_or_b32 v120, v121, 16, v120
	v_lshl_or_b32 v121, v123, 16, v122
	v_add_co_u32_e32 v94, vcc, 0x20000, v108
	s_nop 1
	v_addc_co_u32_e32 v95, vcc, 0, v109, vcc
	global_store_dwordx2 v[94:95], v[120:121], off offset:1024
	s_waitcnt lgkmcnt(0)
	v_lshl_or_b32 v124, v125, 16, v124
	v_lshl_or_b32 v125, v127, 16, v126
	v_add_co_u32_e32 v96, vcc, 0x30000, v108
	s_nop 1
	v_addc_co_u32_e32 v97, vcc, 0, v109, vcc
	global_store_dwordx2 v[96:97], v[124:125], off offset:1024
	s_waitcnt vmcnt(4)
	s_cmp_lg_u32 s101, 0
	s_cbranch_scc1 .Lyt_loop
	s_branch .LBB0_1034
